# WO/F2 residual epilogue stores also write-through (sc1)
# speedup vs baseline: 1.0163x; 1.0031x over previous
.LBB0_43:
	s_lshl_b32 s3, s42, 8
	v_readlane_b32 s20, v252, 26
	s_add_i32 s20, s3, s20
	s_add_i32 s28, s20, 0xffff8000
	v_readlane_b32 s21, v252, 27
	s_lshr_b32 s28, s28, 13
	s_ashr_i32 s21, s20, 11
	s_add_i32 s28, s28, 16
	s_cmp_lt_i32 s20, 0x8000
	s_cselect_b32 s20, s21, s28
	v_add_u32_e32 v172, s3, v1
	v_lshl_or_b32 v98, s43, 8, v174
	s_mul_hi_i32 s21, s20, 0x6000
	s_mulk_i32 s20, 0x6000
	v_ashrrev_i32_e32 v173, 31, v172
	s_add_u32 s20, s45, s20
	v_ashrrev_i32_e32 v99, 31, v98
	v_lshlrev_b64 v[154:155], 12, v[172:173]
	s_addc_u32 s21, s82, s21
	v_lshlrev_b64 v[170:171], 2, v[98:99]
	v_lshl_add_u64 v[154:155], s[40:41], 0, v[154:155]
	v_lshl_add_u64 v[98:99], s[20:21], 0, v[170:171]
	v_lshl_add_u64 v[154:155], v[154:155], 0, v[170:171]
	global_load_dwordx4 v[130:133], v[98:99], off
	global_load_dwordx4 v[122:125], v[98:99], off offset:64
	global_load_dwordx4 v[114:117], v[98:99], off offset:512
	s_nop 0
	global_load_dwordx4 v[98:101], v[98:99], off offset:576
	s_mov_b32 s3, 0x80000
	v_lshl_add_u32 v248, v172, 12, v170
	s_add_u32 s20, s40, 0x0
	s_addc_u32 s21, s41, 0
	global_load_dwordx4 v[176:179], v248, s[20:21]
	global_load_dwordx4 v[180:183], v248, s[20:21] offset:64
	global_load_dwordx4 v[184:187], v248, s[20:21] offset:512
	global_load_dwordx4 v[188:191], v248, s[20:21] offset:576
	s_add_u32 s20, s40, 0x10000
	s_addc_u32 s21, s41, 0
	global_load_dwordx4 v[192:195], v248, s[20:21]
	global_load_dwordx4 v[196:199], v248, s[20:21] offset:64
	global_load_dwordx4 v[208:211], v248, s[20:21] offset:512
	global_load_dwordx4 v[212:215], v248, s[20:21] offset:576
	s_add_u32 s20, s40, 0x20000
	s_addc_u32 s21, s41, 0
	global_load_dwordx4 v[216:219], v248, s[20:21]
	global_load_dwordx4 v[220:223], v248, s[20:21] offset:64
	global_load_dwordx4 v[224:227], v248, s[20:21] offset:512
	global_load_dwordx4 v[228:231], v248, s[20:21] offset:576
	s_add_u32 s20, s40, 0x30000
	s_addc_u32 s21, s41, 0
	global_load_dwordx4 v[232:235], v248, s[20:21]
	global_load_dwordx4 v[236:239], v248, s[20:21] offset:64
	global_load_dwordx4 v[240:243], v248, s[20:21] offset:512
	global_load_dwordx4 v[244:247], v248, s[20:21] offset:576
	s_waitcnt vmcnt(12)
	v_pk_fma_f32 v[144:145], v[144:145], v[132:133], v[178:179]
	v_pk_fma_f32 v[142:143], v[142:143], v[130:131], v[176:177]
	v_pk_fma_f32 v[140:141], v[140:141], v[124:125], v[182:183]
	v_pk_fma_f32 v[138:139], v[138:139], v[122:123], v[180:181]
	v_pk_fma_f32 v[136:137], v[136:137], v[116:117], v[186:187]
	v_pk_fma_f32 v[134:135], v[134:135], v[114:115], v[184:185]
	v_pk_fma_f32 v[128:129], v[128:129], v[100:101], v[190:191]
	v_pk_fma_f32 v[126:127], v[126:127], v[98:99], v[188:189]
	s_add_u32 s48, s40, 0x0
	s_addc_u32 s49, s41, 0
	global_store_dwordx4 v248, v[142:145], s[48:49] sc1
	global_store_dwordx4 v248, v[138:141], s[48:49] offset:64 sc1
	global_store_dwordx4 v248, v[134:137], s[48:49] offset:512 sc1
	global_store_dwordx4 v248, v[126:129], s[48:49] offset:576 sc1
	s_add_u32 s20, s40, 0x80000
	s_addc_u32 s21, s41, 0
	global_load_dwordx4 v[176:179], v248, s[20:21]
	global_load_dwordx4 v[180:183], v248, s[20:21] offset:64
	global_load_dwordx4 v[184:187], v248, s[20:21] offset:512
	global_load_dwordx4 v[188:191], v248, s[20:21] offset:576
	s_waitcnt vmcnt(16)
	v_pk_fma_f32 v[120:121], v[120:121], v[132:133], v[194:195]
	v_pk_fma_f32 v[118:119], v[118:119], v[130:131], v[192:193]
	v_pk_fma_f32 v[112:113], v[112:113], v[124:125], v[198:199]
	v_pk_fma_f32 v[110:111], v[110:111], v[122:123], v[196:197]
	v_pk_fma_f32 v[108:109], v[108:109], v[116:117], v[210:211]
	v_pk_fma_f32 v[106:107], v[106:107], v[114:115], v[208:209]
	v_pk_fma_f32 v[104:105], v[104:105], v[100:101], v[214:215]
	v_pk_fma_f32 v[102:103], v[102:103], v[98:99], v[212:213]
	s_add_u32 s48, s40, 0x10000
	s_addc_u32 s49, s41, 0
	global_store_dwordx4 v248, v[118:121], s[48:49] sc1
	global_store_dwordx4 v248, v[110:113], s[48:49] offset:64 sc1
	global_store_dwordx4 v248, v[106:109], s[48:49] offset:512 sc1
	global_store_dwordx4 v248, v[102:105], s[48:49] offset:576 sc1
	s_add_u32 s20, s40, 0x90000
	s_addc_u32 s21, s41, 0
	global_load_dwordx4 v[192:195], v248, s[20:21]
	global_load_dwordx4 v[196:199], v248, s[20:21] offset:64
	global_load_dwordx4 v[208:211], v248, s[20:21] offset:512
	global_load_dwordx4 v[212:215], v248, s[20:21] offset:576
	s_waitcnt vmcnt(20)
	v_pk_fma_f32 v[96:97], v[96:97], v[132:133], v[218:219]
	v_pk_fma_f32 v[94:95], v[94:95], v[130:131], v[216:217]
	v_pk_fma_f32 v[92:93], v[92:93], v[124:125], v[222:223]
	v_pk_fma_f32 v[90:91], v[90:91], v[122:123], v[220:221]
	v_pk_fma_f32 v[88:89], v[88:89], v[116:117], v[226:227]
	v_pk_fma_f32 v[86:87], v[86:87], v[114:115], v[224:225]
	v_pk_fma_f32 v[84:85], v[84:85], v[100:101], v[230:231]
	v_pk_fma_f32 v[82:83], v[82:83], v[98:99], v[228:229]
	s_add_u32 s48, s40, 0x20000
	s_addc_u32 s49, s41, 0
	global_store_dwordx4 v248, v[94:97], s[48:49] sc1
	global_store_dwordx4 v248, v[90:93], s[48:49] offset:64 sc1
	global_store_dwordx4 v248, v[86:89], s[48:49] offset:512 sc1
	global_store_dwordx4 v248, v[82:85], s[48:49] offset:576 sc1
	s_add_u32 s20, s40, 0xa0000
	s_addc_u32 s21, s41, 0
	global_load_dwordx4 v[216:219], v248, s[20:21]
	global_load_dwordx4 v[220:223], v248, s[20:21] offset:64
	global_load_dwordx4 v[224:227], v248, s[20:21] offset:512
	global_load_dwordx4 v[228:231], v248, s[20:21] offset:576
	s_waitcnt vmcnt(24)
	v_pk_fma_f32 v[80:81], v[80:81], v[132:133], v[234:235]
	v_pk_fma_f32 v[78:79], v[78:79], v[130:131], v[232:233]
	v_pk_fma_f32 v[76:77], v[76:77], v[124:125], v[238:239]
	v_pk_fma_f32 v[74:75], v[74:75], v[122:123], v[236:237]
	v_pk_fma_f32 v[72:73], v[72:73], v[116:117], v[242:243]
	v_pk_fma_f32 v[70:71], v[70:71], v[114:115], v[240:241]
	v_pk_fma_f32 v[68:69], v[68:69], v[100:101], v[246:247]
	v_pk_fma_f32 v[66:67], v[66:67], v[98:99], v[244:245]
	s_add_u32 s48, s40, 0x30000
	s_addc_u32 s49, s41, 0
	global_store_dwordx4 v248, v[78:81], s[48:49] sc1
	global_store_dwordx4 v248, v[74:77], s[48:49] offset:64 sc1
	global_store_dwordx4 v248, v[70:73], s[48:49] offset:512 sc1
	global_store_dwordx4 v248, v[66:69], s[48:49] offset:576 sc1
	s_add_u32 s20, s40, 0xb0000
	s_addc_u32 s21, s41, 0
	global_load_dwordx4 v[232:235], v248, s[20:21]
	global_load_dwordx4 v[236:239], v248, s[20:21] offset:64
	global_load_dwordx4 v[240:243], v248, s[20:21] offset:512
	global_load_dwordx4 v[244:247], v248, s[20:21] offset:576
	s_waitcnt vmcnt(24)
	v_pk_fma_f32 v[64:65], v[64:65], v[132:133], v[178:179]
	v_pk_fma_f32 v[62:63], v[62:63], v[130:131], v[176:177]
	v_pk_fma_f32 v[60:61], v[60:61], v[124:125], v[182:183]
	v_pk_fma_f32 v[58:59], v[58:59], v[122:123], v[180:181]
	v_pk_fma_f32 v[56:57], v[56:57], v[116:117], v[186:187]
	v_pk_fma_f32 v[54:55], v[54:55], v[114:115], v[184:185]
	v_pk_fma_f32 v[52:53], v[52:53], v[100:101], v[190:191]
	v_pk_fma_f32 v[50:51], v[50:51], v[98:99], v[188:189]
	s_add_u32 s48, s40, 0x80000
	s_addc_u32 s49, s41, 0
	global_store_dwordx4 v248, v[62:65], s[48:49] sc1
	global_store_dwordx4 v248, v[58:61], s[48:49] offset:64 sc1
	global_store_dwordx4 v248, v[54:57], s[48:49] offset:512 sc1
	global_store_dwordx4 v248, v[50:53], s[48:49] offset:576 sc1
	s_waitcnt vmcnt(20)
	v_pk_fma_f32 v[48:49], v[48:49], v[132:133], v[194:195]
	v_pk_fma_f32 v[46:47], v[46:47], v[130:131], v[192:193]
	v_pk_fma_f32 v[44:45], v[44:45], v[124:125], v[198:199]
	v_pk_fma_f32 v[42:43], v[42:43], v[122:123], v[196:197]
	v_pk_fma_f32 v[40:41], v[40:41], v[116:117], v[210:211]
	v_pk_fma_f32 v[38:39], v[38:39], v[114:115], v[208:209]
	v_pk_fma_f32 v[36:37], v[36:37], v[100:101], v[214:215]
	v_pk_fma_f32 v[34:35], v[34:35], v[98:99], v[212:213]
	s_add_u32 s48, s40, 0x90000
	s_addc_u32 s49, s41, 0
	global_store_dwordx4 v248, v[46:49], s[48:49] sc1
	global_store_dwordx4 v248, v[42:45], s[48:49] offset:64 sc1
	global_store_dwordx4 v248, v[38:41], s[48:49] offset:512 sc1
	global_store_dwordx4 v248, v[34:37], s[48:49] offset:576 sc1
	s_waitcnt vmcnt(16)
	v_pk_fma_f32 v[32:33], v[32:33], v[132:133], v[218:219]
	v_pk_fma_f32 v[30:31], v[30:31], v[130:131], v[216:217]
	v_pk_fma_f32 v[28:29], v[28:29], v[124:125], v[222:223]
	v_pk_fma_f32 v[26:27], v[26:27], v[122:123], v[220:221]
	v_pk_fma_f32 v[24:25], v[24:25], v[116:117], v[226:227]
	v_pk_fma_f32 v[22:23], v[22:23], v[114:115], v[224:225]
	v_pk_fma_f32 v[20:21], v[20:21], v[100:101], v[230:231]
	v_pk_fma_f32 v[18:19], v[18:19], v[98:99], v[228:229]
	s_add_u32 s48, s40, 0xa0000
	s_addc_u32 s49, s41, 0
	global_store_dwordx4 v248, v[30:33], s[48:49] sc1
	global_store_dwordx4 v248, v[26:29], s[48:49] offset:64 sc1
	global_store_dwordx4 v248, v[22:25], s[48:49] offset:512 sc1
	global_store_dwordx4 v248, v[18:21], s[48:49] offset:576 sc1
	s_waitcnt vmcnt(12)
	v_pk_fma_f32 v[16:17], v[16:17], v[132:133], v[234:235]
	v_pk_fma_f32 v[14:15], v[14:15], v[130:131], v[232:233]
	v_pk_fma_f32 v[12:13], v[12:13], v[124:125], v[238:239]
	v_pk_fma_f32 v[10:11], v[10:11], v[122:123], v[236:237]
	v_pk_fma_f32 v[8:9], v[8:9], v[116:117], v[242:243]
	v_pk_fma_f32 v[6:7], v[6:7], v[114:115], v[240:241]
	v_pk_fma_f32 v[4:5], v[4:5], v[100:101], v[246:247]
	v_pk_fma_f32 v[2:3], v[2:3], v[98:99], v[244:245]
	s_add_u32 s48, s40, 0xb0000
	s_addc_u32 s49, s41, 0
	global_store_dwordx4 v248, v[14:17], s[48:49] sc1
	global_store_dwordx4 v248, v[10:13], s[48:49] offset:64 sc1
	global_store_dwordx4 v248, v[6:9], s[48:49] offset:512 sc1
	global_store_dwordx4 v248, v[2:5], s[48:49] offset:576 sc1
	s_mov_b64 s[20:21], -1
	s_and_b64 vcc, exec, s[36:37]
	s_cbranch_vccnz .LBB0_27
	v_readlane_b32 s20, v252, 38
	v_readlane_b32 s21, v252, 39
	s_andn2_b64 vcc, exec, s[20:21]
	s_cbranch_vccnz .LBB0_26
	s_barrier
	s_branch .LBB0_26

.LBB0_105:
	s_lshl_b32 s2, s2, 8
	v_readlane_b32 s20, v252, 26
	v_readlane_b32 s21, v252, 27
	s_add_i32 s13, s2, s20
	s_add_i32 s21, s13, 0xffff8000
	s_lshr_b32 s21, s21, 13
	s_ashr_i32 s20, s13, 11
	s_add_i32 s21, s21, 16
	s_cmp_lt_i32 s13, 0x8000
	v_add_u32_e32 v172, s2, v1
	v_lshl_or_b32 v170, s99, 8, v174
	s_cselect_b32 s13, s20, s21
	v_ashrrev_i32_e32 v173, 31, v172
	s_mul_hi_i32 s21, s13, 0x6000
	s_mulk_i32 s13, 0x6000
	v_ashrrev_i32_e32 v171, 31, v170
	v_lshlrev_b64 v[154:155], 10, v[172:173]
	s_add_u32 s20, s45, s13
	v_lshl_add_u64 v[154:155], v[154:155], 0, v[170:171]
	s_addc_u32 s21, s82, s21
	v_lshlrev_b64 v[154:155], 2, v[154:155]
	v_lshl_add_u64 v[130:131], v[170:171], 2, s[20:21]
	v_lshl_add_u64 v[180:181], s[30:31], 0, v[154:155]
	global_load_dwordx4 v[142:145], v[130:131], off
	global_load_dwordx4 v[138:141], v[130:131], off offset:64
	global_load_dwordx4 v[134:137], v[130:131], off offset:512
	s_nop 0
	global_load_dwordx4 v[130:133], v[130:131], off offset:576
	s_add_u32 s20, s30, 0x0
	s_addc_u32 s21, s31, 0
	global_load_dwordx4 v[176:179], v154, s[20:21]
	global_load_dwordx4 v[180:183], v154, s[20:21] offset:64
	global_load_dwordx4 v[184:187], v154, s[20:21] offset:512
	global_load_dwordx4 v[188:191], v154, s[20:21] offset:576
	s_add_u32 s20, s30, 0x10000
	s_addc_u32 s21, s31, 0
	global_load_dwordx4 v[192:195], v154, s[20:21]
	global_load_dwordx4 v[196:199], v154, s[20:21] offset:64
	global_load_dwordx4 v[208:211], v154, s[20:21] offset:512
	global_load_dwordx4 v[212:215], v154, s[20:21] offset:576
	s_add_u32 s20, s30, 0x20000
	s_addc_u32 s21, s31, 0
	global_load_dwordx4 v[216:219], v154, s[20:21]
	global_load_dwordx4 v[220:223], v154, s[20:21] offset:64
	global_load_dwordx4 v[224:227], v154, s[20:21] offset:512
	global_load_dwordx4 v[228:231], v154, s[20:21] offset:576
	s_add_u32 s20, s30, 0x30000
	s_addc_u32 s21, s31, 0
	global_load_dwordx4 v[232:235], v154, s[20:21]
	global_load_dwordx4 v[236:239], v154, s[20:21] offset:64
	global_load_dwordx4 v[240:243], v154, s[20:21] offset:512
	global_load_dwordx4 v[244:247], v154, s[20:21] offset:576
	s_waitcnt vmcnt(12)
	v_pk_fma_f32 v[128:129], v[128:129], v[144:145], v[178:179]
	v_pk_fma_f32 v[126:127], v[126:127], v[142:143], v[176:177]
	v_pk_fma_f32 v[124:125], v[124:125], v[140:141], v[182:183]
	v_pk_fma_f32 v[122:123], v[122:123], v[138:139], v[180:181]
	v_pk_fma_f32 v[120:121], v[120:121], v[136:137], v[186:187]
	v_pk_fma_f32 v[118:119], v[118:119], v[134:135], v[184:185]
	v_pk_fma_f32 v[116:117], v[116:117], v[132:133], v[190:191]
	v_pk_fma_f32 v[114:115], v[114:115], v[130:131], v[188:189]
	s_add_u32 s48, s40, 0x0
	s_addc_u32 s49, s41, 0
	global_store_dwordx4 v154, v[126:129], s[48:49] sc1
	global_store_dwordx4 v154, v[122:125], s[48:49] offset:64 sc1
	global_store_dwordx4 v154, v[118:121], s[48:49] offset:512 sc1
	global_store_dwordx4 v154, v[114:117], s[48:49] offset:576 sc1
	s_add_u32 s20, s30, 0x80000
	s_addc_u32 s21, s31, 0
	global_load_dwordx4 v[176:179], v154, s[20:21]
	global_load_dwordx4 v[180:183], v154, s[20:21] offset:64
	global_load_dwordx4 v[184:187], v154, s[20:21] offset:512
	global_load_dwordx4 v[188:191], v154, s[20:21] offset:576
	s_waitcnt vmcnt(16)
	v_pk_fma_f32 v[112:113], v[112:113], v[144:145], v[194:195]
	v_pk_fma_f32 v[110:111], v[110:111], v[142:143], v[192:193]
	v_pk_fma_f32 v[108:109], v[108:109], v[140:141], v[198:199]
	v_pk_fma_f32 v[106:107], v[106:107], v[138:139], v[196:197]
	v_pk_fma_f32 v[104:105], v[104:105], v[136:137], v[210:211]
	v_pk_fma_f32 v[102:103], v[102:103], v[134:135], v[208:209]
	v_pk_fma_f32 v[100:101], v[100:101], v[132:133], v[214:215]
	v_pk_fma_f32 v[98:99], v[98:99], v[130:131], v[212:213]
	s_add_u32 s48, s40, 0x10000
	s_addc_u32 s49, s41, 0
	global_store_dwordx4 v154, v[110:113], s[48:49] sc1
	global_store_dwordx4 v154, v[106:109], s[48:49] offset:64 sc1
	global_store_dwordx4 v154, v[102:105], s[48:49] offset:512 sc1
	global_store_dwordx4 v154, v[98:101], s[48:49] offset:576 sc1
	s_add_u32 s20, s30, 0x90000
	s_addc_u32 s21, s31, 0
	global_load_dwordx4 v[192:195], v154, s[20:21]
	global_load_dwordx4 v[196:199], v154, s[20:21] offset:64
	global_load_dwordx4 v[208:211], v154, s[20:21] offset:512
	global_load_dwordx4 v[212:215], v154, s[20:21] offset:576
	s_waitcnt vmcnt(20)
	v_pk_fma_f32 v[96:97], v[96:97], v[144:145], v[218:219]
	v_pk_fma_f32 v[94:95], v[94:95], v[142:143], v[216:217]
	v_pk_fma_f32 v[92:93], v[92:93], v[140:141], v[222:223]
	v_pk_fma_f32 v[90:91], v[90:91], v[138:139], v[220:221]
	v_pk_fma_f32 v[88:89], v[88:89], v[136:137], v[226:227]
	v_pk_fma_f32 v[86:87], v[86:87], v[134:135], v[224:225]
	v_pk_fma_f32 v[84:85], v[84:85], v[132:133], v[230:231]
	v_pk_fma_f32 v[82:83], v[82:83], v[130:131], v[228:229]
	s_add_u32 s48, s40, 0x20000
	s_addc_u32 s49, s41, 0
	global_store_dwordx4 v154, v[94:97], s[48:49] sc1
	global_store_dwordx4 v154, v[90:93], s[48:49] offset:64 sc1
	global_store_dwordx4 v154, v[86:89], s[48:49] offset:512 sc1
	global_store_dwordx4 v154, v[82:85], s[48:49] offset:576 sc1
	s_add_u32 s20, s30, 0xa0000
	s_addc_u32 s21, s31, 0
	global_load_dwordx4 v[216:219], v154, s[20:21]
	global_load_dwordx4 v[220:223], v154, s[20:21] offset:64
	global_load_dwordx4 v[224:227], v154, s[20:21] offset:512
	global_load_dwordx4 v[228:231], v154, s[20:21] offset:576
	s_waitcnt vmcnt(24)
	v_pk_fma_f32 v[80:81], v[80:81], v[144:145], v[234:235]
	v_pk_fma_f32 v[78:79], v[78:79], v[142:143], v[232:233]
	v_pk_fma_f32 v[76:77], v[76:77], v[140:141], v[238:239]
	v_pk_fma_f32 v[74:75], v[74:75], v[138:139], v[236:237]
	v_pk_fma_f32 v[72:73], v[72:73], v[136:137], v[242:243]
	v_pk_fma_f32 v[70:71], v[70:71], v[134:135], v[240:241]
	v_pk_fma_f32 v[68:69], v[68:69], v[132:133], v[246:247]
	v_pk_fma_f32 v[66:67], v[66:67], v[130:131], v[244:245]
	s_add_u32 s48, s40, 0x30000
	s_addc_u32 s49, s41, 0
	global_store_dwordx4 v154, v[78:81], s[48:49] sc1
	global_store_dwordx4 v154, v[74:77], s[48:49] offset:64 sc1
	global_store_dwordx4 v154, v[70:73], s[48:49] offset:512 sc1
	global_store_dwordx4 v154, v[66:69], s[48:49] offset:576 sc1
	s_add_u32 s20, s30, 0xb0000
	s_addc_u32 s21, s31, 0
	global_load_dwordx4 v[232:235], v154, s[20:21]
	global_load_dwordx4 v[236:239], v154, s[20:21] offset:64
	global_load_dwordx4 v[240:243], v154, s[20:21] offset:512
	global_load_dwordx4 v[244:247], v154, s[20:21] offset:576
	s_waitcnt vmcnt(24)
	v_pk_fma_f32 v[64:65], v[64:65], v[144:145], v[178:179]
	v_pk_fma_f32 v[62:63], v[62:63], v[142:143], v[176:177]
	v_pk_fma_f32 v[60:61], v[60:61], v[140:141], v[182:183]
	v_pk_fma_f32 v[58:59], v[58:59], v[138:139], v[180:181]
	v_pk_fma_f32 v[56:57], v[56:57], v[136:137], v[186:187]
	v_pk_fma_f32 v[54:55], v[54:55], v[134:135], v[184:185]
	v_pk_fma_f32 v[52:53], v[52:53], v[132:133], v[190:191]
	v_pk_fma_f32 v[50:51], v[50:51], v[130:131], v[188:189]
	s_add_u32 s48, s40, 0x80000
	s_addc_u32 s49, s41, 0
	global_store_dwordx4 v154, v[62:65], s[48:49] sc1
	global_store_dwordx4 v154, v[58:61], s[48:49] offset:64 sc1
	global_store_dwordx4 v154, v[54:57], s[48:49] offset:512 sc1
	global_store_dwordx4 v154, v[50:53], s[48:49] offset:576 sc1
	s_waitcnt vmcnt(20)
	v_pk_fma_f32 v[48:49], v[48:49], v[144:145], v[194:195]
	v_pk_fma_f32 v[46:47], v[46:47], v[142:143], v[192:193]
	v_pk_fma_f32 v[44:45], v[44:45], v[140:141], v[198:199]
	v_pk_fma_f32 v[42:43], v[42:43], v[138:139], v[196:197]
	v_pk_fma_f32 v[40:41], v[40:41], v[136:137], v[210:211]
	v_pk_fma_f32 v[38:39], v[38:39], v[134:135], v[208:209]
	v_pk_fma_f32 v[36:37], v[36:37], v[132:133], v[214:215]
	v_pk_fma_f32 v[34:35], v[34:35], v[130:131], v[212:213]
	s_add_u32 s48, s40, 0x90000
	s_addc_u32 s49, s41, 0
	global_store_dwordx4 v154, v[46:49], s[48:49] sc1
	global_store_dwordx4 v154, v[42:45], s[48:49] offset:64 sc1
	global_store_dwordx4 v154, v[38:41], s[48:49] offset:512 sc1
	global_store_dwordx4 v154, v[34:37], s[48:49] offset:576 sc1
	s_waitcnt vmcnt(16)
	v_pk_fma_f32 v[32:33], v[32:33], v[144:145], v[218:219]
	v_pk_fma_f32 v[30:31], v[30:31], v[142:143], v[216:217]
	v_pk_fma_f32 v[28:29], v[28:29], v[140:141], v[222:223]
	v_pk_fma_f32 v[26:27], v[26:27], v[138:139], v[220:221]
	v_pk_fma_f32 v[24:25], v[24:25], v[136:137], v[226:227]
	v_pk_fma_f32 v[22:23], v[22:23], v[134:135], v[224:225]
	v_pk_fma_f32 v[20:21], v[20:21], v[132:133], v[230:231]
	v_pk_fma_f32 v[18:19], v[18:19], v[130:131], v[228:229]
	s_add_u32 s48, s40, 0xa0000
	s_addc_u32 s49, s41, 0
	global_store_dwordx4 v154, v[30:33], s[48:49] sc1
	global_store_dwordx4 v154, v[26:29], s[48:49] offset:64 sc1
	global_store_dwordx4 v154, v[22:25], s[48:49] offset:512 sc1
	global_store_dwordx4 v154, v[18:21], s[48:49] offset:576 sc1
	s_waitcnt vmcnt(12)
	v_pk_fma_f32 v[16:17], v[16:17], v[144:145], v[234:235]
	v_pk_fma_f32 v[14:15], v[14:15], v[142:143], v[232:233]
	v_pk_fma_f32 v[12:13], v[12:13], v[140:141], v[238:239]
	v_pk_fma_f32 v[10:11], v[10:11], v[138:139], v[236:237]
	v_pk_fma_f32 v[8:9], v[8:9], v[136:137], v[242:243]
	v_pk_fma_f32 v[6:7], v[6:7], v[134:135], v[240:241]
	v_pk_fma_f32 v[4:5], v[4:5], v[132:133], v[246:247]
	v_pk_fma_f32 v[2:3], v[2:3], v[130:131], v[244:245]
	s_add_u32 s48, s40, 0xb0000
	s_addc_u32 s49, s41, 0
	global_store_dwordx4 v154, v[14:17], s[48:49] sc1
	global_store_dwordx4 v154, v[10:13], s[48:49] offset:64 sc1
	global_store_dwordx4 v154, v[6:9], s[48:49] offset:512 sc1
	global_store_dwordx4 v154, v[2:5], s[48:49] offset:576 sc1
	s_mov_b64 s[20:21], -1
	s_and_b64 vcc, exec, s[36:37]
	s_cbranch_vccnz .LBB0_89
	v_readlane_b32 s20, v252, 38
	v_readlane_b32 s21, v252, 39
	s_andn2_b64 vcc, exec, s[20:21]
	s_cbranch_vccnz .LBB0_88
	s_barrier
	s_branch .LBB0_88
